# bf16-output GEMM: waves own 64 adjacent columns (weight-tile staging rows remapped); EpiBf16 stores as full 128B lines via DPP row exchange
# speedup vs baseline: 1.0207x; 1.0008x over previous
; __device__ __forceinline__ int tid_fresh() { int t = threadIdx.x; asm volatile("" : "+v"(t)); return t; }
; #define PG8_STAGE(bufoff, gbase, voff) do { _Pragma("unroll") for (int _i = 0; _i < 2; ++_i) \
;         __builtin_amdgcn_global_load_lds((const unsigned*)((const char*)(gbase) + (voff)[_i]), (LAS unsigned*)(lds + (bufoff) + ldsw + _i * 8192), 16, 0, 0); } while (0)
; #define PG8_WAIT_V(n) asm volatile("s_waitcnt vmcnt(" #n ")" ::: "memory")
; template <class Epi>
; __device__ __forceinline__ void gemm_phase(LAS unsigned char* lds, const Gemm g, const StaticOrder& S, const Epi& E) {
;     const int tid = tid_fresh(), wid = __builtin_amdgcn_readfirstlane(tid >> 6), lane = tid & 63, wr = wid >> 2, wc = wid & 3, fr = lane & 15, fq = lane >> 4;
;     const int K = g.K, nt = K / BK, lda = g.lda;
;     unsigned voffA[2], voffB[2];
; #pragma unroll
;     for (int i = 0; i < 2; ++i) { int R, C; stage_rc(tid * 16 + i * 8192, R, C); const int Rb = Epi::PERM ? ((R & ~31) + perm32(R & 31)) : R;
;         voffA[i] = (unsigned)(R * lda + C) * 2u; voffB[i] = (unsigned)(Rb * K + C) * 2u; }
;     const size_t kstep = (size_t)(BK * 2);
;     const size_t hA = (size_t)HALF * lda * 2, hB = (size_t)HALF * K * 2;
;     const size_t tA = 2 * hA, tB = 2 * hB;
;     const unsigned ldsw = (unsigned)wid * 1024u;
;     const int aoff = lds_byte(wr * 64 + fr, fq * 8), boff = lds_byte(wc * 32 + fr, fq * 8);
;     ...
;     Unit cur, nxt; int ui = 0;
;     if (!S.next(0, cur)) return;
;     f32x4 acc[2][2][4][2];
; #pragma unroll
;     for (int a = 0; a < 2; ++a)
; #pragma unroll
;         for (int b = 0; b < 2; ++b)
; #pragma unroll
;             for (int m = 0; m < 4; ++m)
; #pragma unroll
;                 for (int n = 0; n < 2; ++n) acc[a][b][m][n] = (f32x4){0.f, 0.f, 0.f, 0.f};
;     bf16x8 At[4][2], B0[2][2], B1[2][2];
;     const char* cA = (const char*)g.A + (size_t)cur.pm * tA + (g.agrp ? (size_t)(cur.pn >> 1) * 1024 : 0);
;     const char* cB = (const char*)g.Bt + (size_t)cur.pn * tB;
;     PG8_STAGE(PG8_SB(0, 0), cB, voffB); PG8_STAGE(PG8_SB(0, 1), cB + hB, voffB); PG8_STAGE(PG8_SA(0, 0), cA, voffA); PG8_STAGE(PG8_SA(0, 1), cA + hA, voffA);
;     if (wr == 1) PG8_BAR;
;     PG8_WAIT_V(2); PG8_BAR;
;     PG8_STAGE(PG8_SB(1, 0), cB + kstep, voffB); PG8_STAGE(PG8_SA(1, 0), cA + kstep, voffA); PG8_STAGE(PG8_SB(1, 1), cB + hB + kstep, voffB);
;     PG8_WAIT_V(6); PG8_BAR;
.LBB0_418:
	s_andn2_b64 vcc, exec, s[6:7]
	s_cbranch_vccnz .LBB0_634
	v_ashrrev_i32_e32 v1, 31, v12
	v_lshrrev_b32_e32 v1, 26, v1
	v_add_u32_e32 v1, v12, v1
	v_ashrrev_i32_e32 v13, 6, v1
	v_bfe_i32 v1, v12, 27, 1
	v_lshlrev_b32_e32 v0, 4, v12
	v_lshrrev_b32_e32 v1, 22, v1
	v_add_u32_e32 v1, v0, v1
	v_and_b32_e32 v1, 0xfffffc00, v1
	v_sub_u32_e32 v1, v0, v1
	v_lshrrev_b32_e32 v2, 4, v1
	v_bitop3_b32 v2, v2, v1, 32 bitop3:0x6c
	v_ashrrev_i32_e32 v1, 31, v1
	v_lshrrev_b32_e32 v1, 26, v1
	v_add_u32_e32 v1, v2, v1
	s_waitcnt vmcnt(4)
	v_ashrrev_i32_e32 v14, 6, v1
	v_lshlrev_b32_e32 v3, 3, v13
	v_mul_i32_i24_e32 v4, 64, v14
	v_and_b32_e32 v3, -16, v3
	v_sub_u32_e32 v2, v2, v4
	v_add_u32_e32 v1, v14, v3
	v_lshlrev_b32_e32 v3, 5, v13
	v_ashrrev_i16_sdwa v2, v203, sext(v2) dst_sel:DWORD dst_unused:UNUSED_PAD src0_sel:DWORD src1_sel:BYTE_0
	v_and_b32_e32 v3, 32, v3
	v_bfe_i32 v15, v2, 0, 16
	v_add_u32_e32 v2, v3, v15
	v_lshlrev_b32_e32 v3, 1, v1
	v_lshrrev_b32_e32 v4, 2, v1
	v_and_b32_e32 v5, 3, v14
	s_mov_b32 s7, 0x7fffffe0
	v_and_b32_e32 v3, 24, v3
	v_and_b32_e32 v4, 4, v4
	v_and_or_b32 v5, v1, s7, v5
	v_or3_b32 v3, v5, v4, v3
	v_lshlrev_b32_e32 v1, 12, v1
	v_lshl_add_u32 v160, v2, 1, v1
	v_mul_lo_u32 v1, v3, s20
	v_add_u32_e32 v0, 0x2000, v0
	v_add_lshl_u32 v168, v1, v2, 1
	v_ashrrev_i32_e32 v1, 31, v0
	v_lshrrev_b32_e32 v1, 22, v1
	v_add_u32_e32 v1, v0, v1
	v_ashrrev_i32_e32 v16, 10, v1
	v_mul_i32_i24_e32 v1, 0x400, v16
	v_sub_u32_e32 v0, v0, v1
	v_lshrrev_b32_e32 v1, 4, v0
	v_bitop3_b32 v0, v1, v0, 32 bitop3:0x6c
	v_ashrrev_i32_e32 v2, 31, v0
	v_lshrrev_b32_e32 v2, 26, v2
	v_lshlrev_b32_e32 v1, 3, v16
	v_add_u32_e32 v2, v0, v2
	v_and_b32_e32 v1, -16, v1
	v_ashrrev_i32_e32 v17, 6, v2
	s_ashr_i32 s22, s2, 1
	s_ashr_i32 s6, s24, 6
	v_add_u32_e32 v1, v17, v1
	v_and_b32_e32 v4, 3, v17
	s_ashr_i32 s37, s36, 31
	s_ashr_i32 s23, s22, 31
	v_and_or_b32 v4, v1, s7, v4
	s_ashr_i32 s7, s24, 8
	s_lshl_b32 s46, s20, 6
	v_mov_b32_e32 v245, s46
	v_mad_u32_u24 v168, v245, s7, v168
	s_lshl_b32 s47, s20, 9
	s_lshl_b32 s48, s6, 10
	s_lshl_b64 s[18:19], s[36:37], 20
	s_lshl_b64 s[22:23], s[22:23], 10
	s_and_b64 s[26:27], s[10:11], exec
	s_cselect_b32 s21, 0, s23
	s_cselect_b32 s22, 0, s22
	s_ashr_i32 s23, s2, 31
	v_and_b32_e32 v2, 0xc0, v2
	s_mul_i32 s23, s47, s23
	s_mul_hi_u32 s25, s47, s2
	v_sub_u32_e32 v0, v0, v2
	s_add_i32 s25, s25, s23
	s_mul_i32 s23, s47, s2
	v_lshlrev_b32_e32 v3, 5, v16
	v_ashrrev_i16_sdwa v0, v203, sext(v0) dst_sel:DWORD dst_unused:UNUSED_PAD src0_sel:DWORD src1_sel:BYTE_0
	s_add_u32 s38, s8, s23
	v_and_b32_e32 v3, 32, v3
	s_waitcnt vmcnt(3)
	v_bfe_i32 v18, v0, 0, 16
	s_addc_u32 s39, s9, s25
	s_add_i32 s49, s48, 0
	v_add_u32_e32 v0, v3, v18
	v_lshlrev_b32_e32 v2, 1, v1
	v_lshrrev_b32_e32 v3, 2, v1
	s_add_i32 m0, s49, 0x10000
	v_and_b32_e32 v2, 24, v2
	v_and_b32_e32 v3, 4, v3
	global_load_lds_dwordx4 v168, s[38:39]
	s_add_i32 m0, s49, 0x12000
	v_or3_b32 v2, v4, v3, v2
	v_lshlrev_b32_e32 v1, 12, v1
	s_add_u32 s23, s14, s18
	v_lshl_add_u32 v162, v0, 1, v1
	v_mul_lo_u32 v1, v2, s20
	s_addc_u32 s25, s15, s19
	v_add_lshl_u32 v164, v1, v0, 1
	v_mad_u32_u24 v164, v245, s7, v164
	v_lshl_add_u32 v164, v245, 1, v164
	s_add_u32 s18, s38, s46
	global_load_lds_dwordx4 v164, s[38:39]
	s_addc_u32 s19, s39, 0
	s_add_i32 m0, s49, 0x14000
	v_mov_b32_e32 v165, v169
	global_load_lds_dwordx4 v168, s[18:19]
	s_add_i32 m0, s49, 0x16000
	s_add_u32 s40, s23, s22
	s_addc_u32 s41, s25, s21
	s_add_i32 s50, s49, 0x2000
	global_load_lds_dwordx4 v164, s[18:19]
	s_mov_b32 m0, s49
	s_add_u32 s22, s40, 0x80000
	global_load_lds_dwordx4 v160, s[40:41]
	s_mov_b32 m0, s50
	s_addc_u32 s23, s41, 0
	s_add_i32 s51, s49, 0x4000
	global_load_lds_dwordx4 v162, s[40:41]
	s_mov_b32 m0, s51
	s_add_i32 s52, s49, 0x6000
	global_load_lds_dwordx4 v160, s[22:23]
	s_mov_b32 m0, s52
	v_mov_b32_e32 v161, v169
	global_load_lds_dwordx4 v162, s[22:23]
	v_mov_b32_e32 v163, v169
	s_cmp_eq_u32 s7, 1
	v_lshl_add_u64 v[8:9], s[38:39], 0, v[168:169]
	v_lshl_add_u64 v[4:5], s[38:39], 0, v[164:165]
	v_lshl_add_u64 v[2:3], s[18:19], 0, v[168:169]
	v_lshl_add_u64 v[0:1], s[18:19], 0, v[164:165]
	v_lshl_add_u64 v[6:7], s[40:41], 0, v[160:161]
	s_cselect_b64 s[18:19], -1, 0
	s_cmp_lg_u32 s7, 1
	v_lshl_add_u64 v[10:11], s[40:41], 0, v[162:163]
	s_cbranch_scc1 .LBB0_421
	s_barrier
.LBB0_421:
	s_and_b32 s53, s6, 3
	s_lshr_b32 s54, s20, 6
	s_lshl_b32 s6, s7, 13
	s_lshl_b32 s25, s53, 12
	s_add_u32 s20, s74, 0x1b784000
	s_addc_u32 s21, s75, 0
	s_add_u32 s22, s74, 0x4000
	s_addc_u32 s23, s75, 0
	s_add_i32 m0, s49, 0x18000
	v_lshl_add_u64 v[8:9], v[8:9], 0, s[80:81]
	s_waitcnt vmcnt(2)
	s_barrier
	global_load_lds_dwordx4 v[8:9], off
	v_lshl_add_u64 v[4:5], v[4:5], 0, s[80:81]
	s_add_i32 m0, s49, 0x1a000
	s_add_i32 s55, s49, 0x8000
	global_load_lds_dwordx4 v[4:5], off
	v_lshl_add_u64 v[4:5], v[6:7], 0, s[80:81]
	s_mov_b32 m0, s55
	s_add_i32 s56, s49, 0xa000
	global_load_lds_dwordx4 v[4:5], off
	v_lshl_add_u64 v[4:5], v[10:11], 0, s[80:81]
	s_mov_b32 m0, s56
	v_lshl_add_u64 v[2:3], v[2:3], 0, s[80:81]
	global_load_lds_dwordx4 v[4:5], off
	s_add_i32 m0, s49, 0x1c000
	v_lshl_add_u64 v[0:1], v[0:1], 0, s[80:81]
	global_load_lds_dwordx4 v[2:3], off
	s_add_i32 m0, s49, 0x1e000
	s_add_i32 s57, s54, -2
	global_load_lds_dwordx4 v[0:1], off
	v_bfe_u32 v0, v12, 4, 2
	v_and_b32_e32 v1, 15, v12
	v_lshlrev_b32_e32 v3, 4, v0
	v_lshl_or_b32 v206, s7, 6, v1
	v_lshl_or_b32 v1, v1, 6, v3
	v_lshlrev_b32_e32 v3, 2, v12
	v_and_b32_e32 v3, 32, v3
	s_cmpk_lt_u32 s24, 0x100
	v_bitop3_b32 v207, v1, s25, v3 bitop3:0xde
	v_add_u32_e32 v240, 0x10000, v207
	v_add_u32_e32 v241, 0x80, v168
	v_add_u32_e32 v242, 0x80, v164
	v_add_u32_e32 v243, 0x80, v160
	v_add_u32_e32 v244, 0x80, v162
	s_cselect_b64 s[24:25], -1, 0
	s_ashr_i32 s59, s44, 31
	s_ashr_i32 s60, s45, 31
	s_lshr_b32 s61, s42, 5
	s_and_b64 s[4:5], s[4:5], exec
	s_cselect_b32 s63, 2, 3
	s_cselect_b32 s62, 4, 8
	s_lshl_b32 s64, s17, s63
	v_bitop3_b32 v4, v1, s6, v3 bitop3:0xde
	v_cvt_f32_u32_e32 v1, s64
	v_lshlrev_b32_e32 v2, 3, v0
	v_cmp_eq_u32_e64 s[4:5], 0, v0
	v_lshlrev_b32_e32 v0, 5, v0
	v_rcp_iflag_f32_e32 v3, v1
	v_mov_b32_e32 v1, v169
	v_lshl_add_u64 v[174:175], s[0:1], 0, v[0:1]
	v_lshlrev_b32_e32 v0, 15, v13
	v_mul_f32_e32 v3, 0x4f7ffffe, v3
	v_cvt_u32_f32_e32 v3, v3
	v_and_b32_e32 v0, 0xffff0000, v0
	v_lshl_add_u32 v0, v14, 12, v0
	v_and_b32_e32 v1, 1, v13
	v_lshl_or_b32 v0, v1, 6, v0
	s_cmp_lg_u64 s[0:1], 0
	v_lshl_add_u32 v176, v15, 1, v0
	v_lshlrev_b32_e32 v0, 15, v16
	s_cselect_b64 s[26:27], -1, 0
	s_sub_i32 s0, 0, s64
	v_readfirstlane_b32 s1, v3
	v_and_b32_e32 v0, 0xffff0000, v0
	s_waitcnt vmcnt(6)
	s_mul_i32 s0, s0, s1
	v_lshl_add_u32 v0, v17, 12, v0
	v_and_b32_e32 v1, 1, v16
	s_mul_hi_u32 s0, s1, s0
	v_lshl_or_b32 v0, v1, 6, v0
	s_mov_b32 s58, 0
	s_mov_b32 s17, s3
	v_lshl_or_b32 v208, s53, 6, v2
	s_add_i32 s65, s1, s0
	v_mov_b32_e32 v177, v169
	v_lshl_add_u32 v178, v18, 1, v0
	v_mov_b32_e32 v179, v169
	v_add_u32_e32 v209, 0, v4
	s_barrier
	s_branch .LBB0_424

;     __device__ __forceinline__ void operator()(const f32x4 (&acc)[2][2][4][2], const Unit& u, int wr, int wc, int fr, int fq) const {
;     ...
;                 const int row = row0 + ai * HALF + m * 16;
;                 bf16_t* rowp = O + (size_t)row * ldc + col0;
;                 float ss = 0.f;
;                 const float rs = rsv[ai * 4 + m];
; #pragma unroll
;                 for (int bj = 0; bj < 2; ++bj) {
;                     f32x4 v0 = acc[ai][bj][m][0] * rs, v1 = acc[ai][bj][m][1] * rs;
;                     if (act == ACT_GELU_VSS) {
;                         f32x2 a = gelu_pk((f32x2){v0[0], v0[1]}), b = gelu_pk((f32x2){v0[2], v0[3]}), c = gelu_pk((f32x2){v1[0], v1[1]}), d = gelu_pk((f32x2){v1[2], v1[3]});
;                         v0 = (f32x4){a.x, a.y, b.x, b.y}; v1 = (f32x4){c.x, c.y, d.x, d.y};
;                         ss += (v0[0] * v0[0] + v0[1] * v0[1]) + (v0[2] * v0[2] + v0[3] * v0[3]) + (v1[0] * v1[0] + v1[1] * v1[1]) + (v1[2] * v1[2] + v1[3] * v1[3]);
;                     } else if (act == ACT_RELU2) {
; #pragma unroll
;                         for (int j = 0; j < 4; ++j) { const float a = fmaxf(v0[j], 0.f), b = fmaxf(v1[j], 0.f); v0[j] = a * a; v1[j] = b * b; }
;                     } else if (act == ACT_COLSCALE) {
;                         v0 = v0 * *(const f32x4*)(colscale + col0 + bj * HALF); v1 = v1 * *(const f32x4*)(colscale + col0 + bj * HALF + 4);
.LBB0_437:
	v_bfe_u32 v235, v206, 3, 1
	v_mov_b32_e32 v234, s42
	v_add_u32_e32 v235, -1, v235
	v_lshlrev_b32_e32 v234, 4, v234
	v_not_b32_e32 v227, v235
	v_sub_u32_e32 v226, 64, v234
	v_add_u32_e32 v228, 64, v234
	v_and_b32_e32 v226, v227, v226
	v_and_b32_e32 v228, v235, v228
	v_mov_b32_e32 v229, 0
	v_lshl_or_b32 v130, s2, 8, v208
	v_ashrrev_i32_e32 v131, 31, v130
	v_pk_mul_f32 v[126:127], v[126:127], v[194:195] op_sel_hi:[1,0]
	v_pk_mul_f32 v[124:125], v[124:125], v[194:195] op_sel_hi:[1,0]
	v_pk_mul_f32 v[122:123], v[122:123], v[194:195] op_sel_hi:[1,0]
	v_pk_mul_f32 v[120:121], v[120:121], v[194:195] op_sel_hi:[1,0]
	s_cmp_lt_i32 s43, 2
	s_mov_b64 s[0:1], -1
	s_cbranch_scc1 .LBB0_443
	s_cmp_gt_i32 s43, 2
	s_cbranch_scc0 .LBB0_440
	v_lshl_add_u64 v[132:133], v[130:131], 2, s[96:97]
	global_load_dwordx4 v[138:141], v[132:133], off
	global_load_dwordx4 v[148:151], v[132:133], off offset:16
	s_mov_b64 s[0:1], 0
	s_waitcnt vmcnt(0)
	v_pk_mul_f32 v[132:133], v[126:127], v[140:141]
	v_pk_mul_f32 v[134:135], v[124:125], v[138:139]
	v_pk_mul_f32 v[138:139], v[122:123], v[150:151]
	v_pk_mul_f32 v[140:141], v[120:121], v[148:149]

; __device__ __forceinline__ unsigned cvt_pk_bf16(float lo, float hi) { unsigned r; asm volatile("v_cvt_pk_bf16_f32 %0, %1, %2" : "=v"(r) : "v"(lo), "v"(hi)); return r; }
;     __device__ __forceinline__ void operator()(const f32x4 (&acc)[2][2][4][2], const Unit& u, int wr, int wc, int fr, int fq) const {
;     ...
;                 const int row = row0 + ai * HALF + m * 16;
;                 bf16_t* rowp = O + (size_t)row * ldc + col0;
;                 float ss = 0.f;
;                 const float rs = rsv[ai * 4 + m];
; #pragma unroll
;                 for (int bj = 0; bj < 2; ++bj) {
;                     f32x4 v0 = acc[ai][bj][m][0] * rs, v1 = acc[ai][bj][m][1] * rs;
;                     if (act == ACT_GELU_VSS) {
;                         f32x2 a = gelu_pk((f32x2){v0[0], v0[1]}), b = gelu_pk((f32x2){v0[2], v0[3]}), c = gelu_pk((f32x2){v1[0], v1[1]}), d = gelu_pk((f32x2){v1[2], v1[3]});
;                         v0 = (f32x4){a.x, a.y, b.x, b.y}; v1 = (f32x4){c.x, c.y, d.x, d.y};
;                         ss += (v0[0] * v0[0] + v0[1] * v0[1]) + (v0[2] * v0[2] + v0[3] * v0[3]) + (v1[0] * v1[0] + v1[1] * v1[1]) + (v1[2] * v1[2] + v1[3] * v1[3]);
;                     } else if (act == ACT_RELU2) {
; #pragma unroll
;                         for (int j = 0; j < 4; ++j) { const float a = fmaxf(v0[j], 0.f), b = fmaxf(v1[j], 0.f); v0[j] = a * a; v1[j] = b * b; }
;                     } else if (act == ACT_COLSCALE) {
;                         v0 = v0 * *(const f32x4*)(colscale + col0 + bj * HALF); v1 = v1 * *(const f32x4*)(colscale + col0 + bj * HALF + 4);
;                     }
;                     u32x4 w; w.x = cvt_pk_bf16(v0[0], v0[1]); w.y = cvt_pk_bf16(v0[2], v0[3]); w.z = cvt_pk_bf16(v1[0], v1[1]); w.w = cvt_pk_bf16(v1[2], v1[3]);
;                     *(u32x4*)(rowp + bj * HALF) = w;
.LBB0_447:
	v_mad_u64_u32 v[120:121], s[0:1], v180, s42, 0
	v_mov_b32_e32 v122, v121
	v_mad_u64_u32 v[122:123], s[0:1], v181, s42, v[122:123]
	v_mov_b32_e32 v121, v122
	v_lshl_add_u64 v[120:121], v[120:121], 1, s[20:21]
	v_lshl_add_u64 v[120:121], v[130:131], 1, v[120:121]
	v_cvt_pk_bf16_f32 v122, v134, v135
	v_cvt_pk_bf16_f32 v123, v132, v133
	v_cvt_pk_bf16_f32 v124, v140, v141
	v_cvt_pk_bf16_f32 v125, v138, v139
	v_mov_b32_e32 v210, v122
	v_mov_b32_e32 v211, v123
	v_mov_b32_e32 v212, v124
	v_mov_b32_e32 v213, v125
	v_mov_b32_e32 v195, v194
	v_pk_mul_f32 v[116:117], v[116:117], v[194:195]
	v_mov_b32_e32 v122, v194
	v_mov_b32_e32 v123, v194
	v_pk_mul_f32 v[118:119], v[118:119], v[122:123]
	v_pk_mul_f32 v[114:115], v[114:115], v[122:123]
	v_pk_mul_f32 v[112:113], v[112:113], v[194:195]
	s_cmp_lt_i32 s43, 2
	s_mov_b64 s[0:1], -1
	s_cbranch_scc1 .LBB0_453
	s_cmp_gt_i32 s43, 2
	s_cbranch_scc0 .LBB0_450
	v_lshl_add_u64 v[122:123], v[130:131], 2, s[96:97]
	global_load_dwordx4 v[124:127], v[122:123], off offset:128
	global_load_dwordx4 v[132:135], v[122:123], off offset:144
	s_mov_b64 s[0:1], 0
	s_waitcnt vmcnt(0)
	v_pk_mul_f32 v[122:123], v[118:119], v[126:127]
	v_pk_mul_f32 v[124:125], v[116:117], v[124:125]
	v_pk_mul_f32 v[126:127], v[114:115], v[134:135]
	v_pk_mul_f32 v[132:133], v[112:113], v[132:133]

; __device__ __forceinline__ unsigned cvt_pk_bf16(float lo, float hi) { unsigned r; asm volatile("v_cvt_pk_bf16_f32 %0, %1, %2" : "=v"(r) : "v"(lo), "v"(hi)); return r; }
;     __device__ __forceinline__ void operator()(const f32x4 (&acc)[2][2][4][2], const Unit& u, int wr, int wc, int fr, int fq) const {
;     ...
;                     u32x4 w; w.x = cvt_pk_bf16(v0[0], v0[1]); w.y = cvt_pk_bf16(v0[2], v0[3]); w.z = cvt_pk_bf16(v1[0], v1[1]); w.w = cvt_pk_bf16(v1[2], v1[3]);
;                     *(u32x4*)(rowp + bj * HALF) = w;
;                 }
;                 if (do_vss) { ss += __shfl_xor(ss, 16); ss += __shfl_xor(ss, 32); if (fq == 0) vss[(size_t)row * 32 + (u.pn - 8) * 4 + wc] = ss; }
.LBB0_457:
	s_lshl_b32 s0, s2, 2
	s_sub_i32 s36, s0, 32
	s_ashr_i32 s37, s36, 31
	s_cmp_gt_i32 s2, 7
	s_cselect_b64 s[0:1], -1, 0
	s_and_b64 s[38:39], s[12:13], s[0:1]
	v_cndmask_b32_e64 v116, 0, 1, s[38:39]
	v_cmp_ne_u32_e64 s[0:1], 1, v116
	s_andn2_b64 vcc, exec, s[38:39]
	v_cvt_pk_bf16_f32 v112, v124, v125
	v_cvt_pk_bf16_f32 v113, v122, v123
	v_cvt_pk_bf16_f32 v114, v132, v133
	v_cvt_pk_bf16_f32 v115, v126, v127
	s_nop 1
	v_mov_b32_dpp v214, v112 row_ror:8 row_mask:0xf bank_mask:0xf
	v_mov_b32_dpp v215, v113 row_ror:8 row_mask:0xf bank_mask:0xf
	v_mov_b32_dpp v216, v114 row_ror:8 row_mask:0xf bank_mask:0xf
	v_mov_b32_dpp v217, v115 row_ror:8 row_mask:0xf bank_mask:0xf
	v_bfi_b32 v218, v235, v210, v214
	v_bfi_b32 v219, v235, v211, v215
	v_bfi_b32 v220, v235, v212, v216
	v_bfi_b32 v221, v235, v213, v217
	v_bfi_b32 v222, v235, v214, v210
	v_bfi_b32 v223, v235, v215, v211
	v_bfi_b32 v224, v235, v216, v212
	v_bfi_b32 v225, v235, v217, v213
	v_lshl_add_u64 v[230:231], v[120:121], 0, v[226:227]
	v_lshl_add_u64 v[232:233], v[120:121], 0, v[228:229]
	global_store_dwordx4 v[230:231], v[218:221], off
	global_store_dwordx4 v[232:233], v[222:225], off
	s_cbranch_vccnz .LBB0_461
	s_nop 0
	v_and_b32_e32 v113, 64, v167
	v_xor_b32_e32 v112, 16, v167
	v_add_u32_e32 v113, 64, v113
	v_cmp_lt_i32_e32 vcc, v112, v113
	v_xor_b32_e32 v114, 32, v167
	s_nop 0
	v_cndmask_b32_e32 v112, v167, v112, vcc
	v_lshlrev_b32_e32 v112, 2, v112
	ds_bpermute_b32 v112, v112, v129
	v_cmp_lt_i32_e32 vcc, v114, v113
	s_waitcnt lgkmcnt(0)
	v_add_f32_e32 v112, v129, v112
	v_cndmask_b32_e32 v113, v167, v114, vcc
	v_lshlrev_b32_e32 v113, 2, v113
	ds_bpermute_b32 v113, v113, v112
	s_and_saveexec_b64 s[38:39], s[4:5]
	s_cbranch_execz .LBB0_460
	v_lshlrev_b64 v[114:115], 7, v[180:181]
	v_lshl_add_u64 v[114:115], s[22:23], 0, v[114:115]
	v_lshl_add_u64 v[114:115], s[36:37], 2, v[114:115]
	s_lshl_b32 s2, s53, 2
	v_lshl_add_u64 v[114:115], v[114:115], 0, s[2:3]
	s_waitcnt lgkmcnt(0)
	v_add_f32_e32 v112, v112, v113
	global_store_dword v[114:115], v112, off

; __device__ __forceinline__ unsigned cvt_pk_bf16(float lo, float hi) { unsigned r; asm volatile("v_cvt_pk_bf16_f32 %0, %1, %2" : "=v"(r) : "v"(lo), "v"(hi)); return r; }
;     __device__ __forceinline__ void operator()(const f32x4 (&acc)[2][2][4][2], const Unit& u, int wr, int wc, int fr, int fq) const {
;     ...
;                 const int row = row0 + ai * HALF + m * 16;
;                 bf16_t* rowp = O + (size_t)row * ldc + col0;
;                 float ss = 0.f;
;                 const float rs = rsv[ai * 4 + m];
; #pragma unroll
;                 for (int bj = 0; bj < 2; ++bj) {
;                     f32x4 v0 = acc[ai][bj][m][0] * rs, v1 = acc[ai][bj][m][1] * rs;
;                     if (act == ACT_GELU_VSS) {
;                         f32x2 a = gelu_pk((f32x2){v0[0], v0[1]}), b = gelu_pk((f32x2){v0[2], v0[3]}), c = gelu_pk((f32x2){v1[0], v1[1]}), d = gelu_pk((f32x2){v1[2], v1[3]});
;                         v0 = (f32x4){a.x, a.y, b.x, b.y}; v1 = (f32x4){c.x, c.y, d.x, d.y};
;                         ss += (v0[0] * v0[0] + v0[1] * v0[1]) + (v0[2] * v0[2] + v0[3] * v0[3]) + (v1[0] * v1[0] + v1[1] * v1[1]) + (v1[2] * v1[2] + v1[3] * v1[3]);
;                     } else if (act == ACT_RELU2) {
; #pragma unroll
;                         for (int j = 0; j < 4; ++j) { const float a = fmaxf(v0[j], 0.f), b = fmaxf(v1[j], 0.f); v0[j] = a * a; v1[j] = b * b; }
;                     } else if (act == ACT_COLSCALE) {
;                         v0 = v0 * *(const f32x4*)(colscale + col0 + bj * HALF); v1 = v1 * *(const f32x4*)(colscale + col0 + bj * HALF + 4);
;                     }
;                     u32x4 w; w.x = cvt_pk_bf16(v0[0], v0[1]); w.y = cvt_pk_bf16(v0[2], v0[3]); w.z = cvt_pk_bf16(v1[0], v1[1]); w.w = cvt_pk_bf16(v1[2], v1[3]);
;                     *(u32x4*)(rowp + bj * HALF) = w;
.LBB0_471:
	v_mad_u64_u32 v[104:105], s[38:39], v188, s42, 0
	v_mov_b32_e32 v106, v105
	v_mad_u64_u32 v[106:107], s[38:39], v189, s42, v[106:107]
	v_mov_b32_e32 v105, v106
	v_lshl_add_u64 v[104:105], v[104:105], 1, s[20:21]
	v_lshl_add_u64 v[104:105], v[130:131], 1, v[104:105]
	v_cvt_pk_bf16_f32 v106, v114, v115
	s_waitcnt lgkmcnt(0)
	v_cvt_pk_bf16_f32 v107, v112, v113
	v_cvt_pk_bf16_f32 v108, v118, v119
	v_cvt_pk_bf16_f32 v109, v116, v117
	v_mov_b32_e32 v210, v106
	v_mov_b32_e32 v211, v107
	v_mov_b32_e32 v212, v108
	v_mov_b32_e32 v213, v109
	v_mov_b32_e32 v193, v192
	v_pk_mul_f32 v[100:101], v[100:101], v[192:193]
	v_mov_b32_e32 v106, v192
	v_mov_b32_e32 v107, v192
	v_pk_mul_f32 v[102:103], v[102:103], v[106:107]
	v_pk_mul_f32 v[98:99], v[98:99], v[106:107]
	v_pk_mul_f32 v[96:97], v[96:97], v[192:193]
	s_cmp_lt_i32 s43, 2
	s_mov_b64 s[38:39], -1
	s_cbranch_scc1 .LBB0_477
	s_cmp_gt_i32 s43, 2
	s_cbranch_scc0 .LBB0_474
	v_lshl_add_u64 v[106:107], v[130:131], 2, s[96:97]
	global_load_dwordx4 v[108:111], v[106:107], off offset:128
	global_load_dwordx4 v[112:115], v[106:107], off offset:144
	s_mov_b64 s[38:39], 0
	s_waitcnt vmcnt(0)
	v_pk_mul_f32 v[106:107], v[102:103], v[110:111]
	v_pk_mul_f32 v[108:109], v[100:101], v[108:109]
	v_pk_mul_f32 v[110:111], v[98:99], v[114:115]
	v_pk_mul_f32 v[112:113], v[96:97], v[112:113]

; __device__ __forceinline__ unsigned cvt_pk_bf16(float lo, float hi) { unsigned r; asm volatile("v_cvt_pk_bf16_f32 %0, %1, %2" : "=v"(r) : "v"(lo), "v"(hi)); return r; }
;     __device__ __forceinline__ void operator()(const f32x4 (&acc)[2][2][4][2], const Unit& u, int wr, int wc, int fr, int fq) const {
;     ...
;                     u32x4 w; w.x = cvt_pk_bf16(v0[0], v0[1]); w.y = cvt_pk_bf16(v0[2], v0[3]); w.z = cvt_pk_bf16(v1[0], v1[1]); w.w = cvt_pk_bf16(v1[2], v1[3]);
;                     *(u32x4*)(rowp + bj * HALF) = w;
;                 }
;                 if (do_vss) { ss += __shfl_xor(ss, 16); ss += __shfl_xor(ss, 32); if (fq == 0) vss[(size_t)row * 32 + (u.pn - 8) * 4 + wc] = ss; }
.LBB0_481:
	s_and_b64 vcc, exec, s[0:1]
	v_cvt_pk_bf16_f32 v96, v108, v109
	v_cvt_pk_bf16_f32 v97, v106, v107
	v_cvt_pk_bf16_f32 v98, v112, v113
	v_cvt_pk_bf16_f32 v99, v110, v111
	s_nop 1
	v_mov_b32_dpp v214, v96 row_ror:8 row_mask:0xf bank_mask:0xf
	v_mov_b32_dpp v215, v97 row_ror:8 row_mask:0xf bank_mask:0xf
	v_mov_b32_dpp v216, v98 row_ror:8 row_mask:0xf bank_mask:0xf
	v_mov_b32_dpp v217, v99 row_ror:8 row_mask:0xf bank_mask:0xf
	v_bfi_b32 v218, v235, v210, v214
	v_bfi_b32 v219, v235, v211, v215
	v_bfi_b32 v220, v235, v212, v216
	v_bfi_b32 v221, v235, v213, v217
	v_bfi_b32 v222, v235, v214, v210
	v_bfi_b32 v223, v235, v215, v211
	v_bfi_b32 v224, v235, v216, v212
	v_bfi_b32 v225, v235, v217, v213
	v_lshl_add_u64 v[230:231], v[104:105], 0, v[226:227]
	v_lshl_add_u64 v[232:233], v[104:105], 0, v[228:229]
	global_store_dwordx4 v[230:231], v[218:221], off
	global_store_dwordx4 v[232:233], v[222:225], off
	s_cbranch_vccnz .LBB0_485
	s_nop 0
	v_and_b32_e32 v97, 64, v167
	v_xor_b32_e32 v96, 16, v167
	v_add_u32_e32 v97, 64, v97
	v_cmp_lt_i32_e32 vcc, v96, v97
	v_xor_b32_e32 v98, 32, v167
	s_nop 0
	v_cndmask_b32_e32 v96, v167, v96, vcc
	v_lshlrev_b32_e32 v96, 2, v96
	ds_bpermute_b32 v96, v96, v120
	v_cmp_lt_i32_e32 vcc, v98, v97
	s_waitcnt lgkmcnt(0)
	v_add_f32_e32 v96, v120, v96
	v_cndmask_b32_e32 v97, v167, v98, vcc
	v_lshlrev_b32_e32 v97, 2, v97
	ds_bpermute_b32 v97, v97, v96
	s_and_saveexec_b64 s[38:39], s[4:5]
	s_cbranch_execz .LBB0_484
	v_lshlrev_b64 v[98:99], 7, v[188:189]
	v_lshl_add_u64 v[98:99], s[22:23], 0, v[98:99]
	v_lshl_add_u64 v[98:99], s[36:37], 2, v[98:99]
	s_lshl_b32 s2, s53, 2
	v_lshl_add_u64 v[98:99], v[98:99], 0, s[2:3]
	s_waitcnt lgkmcnt(0)
	v_add_f32_e32 v96, v96, v97
	global_store_dword v[98:99], v96, off

; __device__ __forceinline__ unsigned cvt_pk_bf16(float lo, float hi) { unsigned r; asm volatile("v_cvt_pk_bf16_f32 %0, %1, %2" : "=v"(r) : "v"(lo), "v"(hi)); return r; }
;     __device__ __forceinline__ void operator()(const f32x4 (&acc)[2][2][4][2], const Unit& u, int wr, int wc, int fr, int fq) const {
;     ...
;                 const int row = row0 + ai * HALF + m * 16;
;                 bf16_t* rowp = O + (size_t)row * ldc + col0;
;                 float ss = 0.f;
;                 const float rs = rsv[ai * 4 + m];
; #pragma unroll
;                 for (int bj = 0; bj < 2; ++bj) {
;                     f32x4 v0 = acc[ai][bj][m][0] * rs, v1 = acc[ai][bj][m][1] * rs;
;                     if (act == ACT_GELU_VSS) {
;                         f32x2 a = gelu_pk((f32x2){v0[0], v0[1]}), b = gelu_pk((f32x2){v0[2], v0[3]}), c = gelu_pk((f32x2){v1[0], v1[1]}), d = gelu_pk((f32x2){v1[2], v1[3]});
;                         v0 = (f32x4){a.x, a.y, b.x, b.y}; v1 = (f32x4){c.x, c.y, d.x, d.y};
;                         ss += (v0[0] * v0[0] + v0[1] * v0[1]) + (v0[2] * v0[2] + v0[3] * v0[3]) + (v1[0] * v1[0] + v1[1] * v1[1]) + (v1[2] * v1[2] + v1[3] * v1[3]);
;                     } else if (act == ACT_RELU2) {
; #pragma unroll
;                         for (int j = 0; j < 4; ++j) { const float a = fmaxf(v0[j], 0.f), b = fmaxf(v1[j], 0.f); v0[j] = a * a; v1[j] = b * b; }
;                     } else if (act == ACT_COLSCALE) {
;                         v0 = v0 * *(const f32x4*)(colscale + col0 + bj * HALF); v1 = v1 * *(const f32x4*)(colscale + col0 + bj * HALF + 4);
;                     }
;                     u32x4 w; w.x = cvt_pk_bf16(v0[0], v0[1]); w.y = cvt_pk_bf16(v0[2], v0[3]); w.z = cvt_pk_bf16(v1[0], v1[1]); w.w = cvt_pk_bf16(v1[2], v1[3]);
;                     *(u32x4*)(rowp + bj * HALF) = w;
.LBB0_495:
	v_mad_u64_u32 v[88:89], s[38:39], v184, s42, 0
	v_mov_b32_e32 v90, v89
	v_mad_u64_u32 v[90:91], s[38:39], v185, s42, v[90:91]
	v_mov_b32_e32 v89, v90
	v_lshl_add_u64 v[88:89], v[88:89], 1, s[20:21]
	v_lshl_add_u64 v[88:89], v[130:131], 1, v[88:89]
	v_cvt_pk_bf16_f32 v90, v98, v99
	s_waitcnt lgkmcnt(0)
	v_cvt_pk_bf16_f32 v91, v96, v97
	v_cvt_pk_bf16_f32 v92, v102, v103
	v_cvt_pk_bf16_f32 v93, v100, v101
	v_mov_b32_e32 v210, v90
	v_mov_b32_e32 v211, v91
	v_mov_b32_e32 v212, v92
	v_mov_b32_e32 v213, v93
	v_mov_b32_e32 v191, v190
	v_pk_mul_f32 v[84:85], v[84:85], v[190:191]
	v_mov_b32_e32 v90, v190
	v_mov_b32_e32 v91, v190
	v_pk_mul_f32 v[86:87], v[86:87], v[90:91]
	v_pk_mul_f32 v[82:83], v[82:83], v[90:91]
	v_pk_mul_f32 v[80:81], v[80:81], v[190:191]
	s_cmp_lt_i32 s43, 2
	s_mov_b64 s[38:39], -1
	s_cbranch_scc1 .LBB0_501
	s_cmp_gt_i32 s43, 2
	s_cbranch_scc0 .LBB0_498
	v_lshl_add_u64 v[90:91], v[130:131], 2, s[96:97]
	global_load_dwordx4 v[92:95], v[90:91], off offset:128
	global_load_dwordx4 v[96:99], v[90:91], off offset:144
	s_mov_b64 s[38:39], 0
	s_waitcnt vmcnt(0)
	v_pk_mul_f32 v[90:91], v[86:87], v[94:95]
	v_pk_mul_f32 v[92:93], v[84:85], v[92:93]
	v_pk_mul_f32 v[94:95], v[82:83], v[98:99]
	v_pk_mul_f32 v[96:97], v[80:81], v[96:97]

; __device__ __forceinline__ unsigned cvt_pk_bf16(float lo, float hi) { unsigned r; asm volatile("v_cvt_pk_bf16_f32 %0, %1, %2" : "=v"(r) : "v"(lo), "v"(hi)); return r; }
;     __device__ __forceinline__ void operator()(const f32x4 (&acc)[2][2][4][2], const Unit& u, int wr, int wc, int fr, int fq) const {
;     ...
;                     u32x4 w; w.x = cvt_pk_bf16(v0[0], v0[1]); w.y = cvt_pk_bf16(v0[2], v0[3]); w.z = cvt_pk_bf16(v1[0], v1[1]); w.w = cvt_pk_bf16(v1[2], v1[3]);
;                     *(u32x4*)(rowp + bj * HALF) = w;
;                 }
;                 if (do_vss) { ss += __shfl_xor(ss, 16); ss += __shfl_xor(ss, 32); if (fq == 0) vss[(size_t)row * 32 + (u.pn - 8) * 4 + wc] = ss; }
.LBB0_505:
	s_and_b64 vcc, exec, s[0:1]
	v_cvt_pk_bf16_f32 v80, v92, v93
	v_cvt_pk_bf16_f32 v81, v90, v91
	v_cvt_pk_bf16_f32 v82, v96, v97
	v_cvt_pk_bf16_f32 v83, v94, v95
	s_nop 1
	v_mov_b32_dpp v214, v80 row_ror:8 row_mask:0xf bank_mask:0xf
	v_mov_b32_dpp v215, v81 row_ror:8 row_mask:0xf bank_mask:0xf
	v_mov_b32_dpp v216, v82 row_ror:8 row_mask:0xf bank_mask:0xf
	v_mov_b32_dpp v217, v83 row_ror:8 row_mask:0xf bank_mask:0xf
	v_bfi_b32 v218, v235, v210, v214
	v_bfi_b32 v219, v235, v211, v215
	v_bfi_b32 v220, v235, v212, v216
	v_bfi_b32 v221, v235, v213, v217
	v_bfi_b32 v222, v235, v214, v210
	v_bfi_b32 v223, v235, v215, v211
	v_bfi_b32 v224, v235, v216, v212
	v_bfi_b32 v225, v235, v217, v213
	v_lshl_add_u64 v[230:231], v[88:89], 0, v[226:227]
	v_lshl_add_u64 v[232:233], v[88:89], 0, v[228:229]
	global_store_dwordx4 v[230:231], v[218:221], off
	global_store_dwordx4 v[232:233], v[222:225], off
	s_cbranch_vccnz .LBB0_509
	s_nop 0
	v_and_b32_e32 v81, 64, v167
	v_xor_b32_e32 v80, 16, v167
	v_add_u32_e32 v81, 64, v81
	v_cmp_lt_i32_e32 vcc, v80, v81
	v_xor_b32_e32 v82, 32, v167
	s_nop 0
	v_cndmask_b32_e32 v80, v167, v80, vcc
	v_lshlrev_b32_e32 v80, 2, v80
	ds_bpermute_b32 v80, v80, v104
	v_cmp_lt_i32_e32 vcc, v82, v81
	s_waitcnt lgkmcnt(0)
	v_add_f32_e32 v80, v104, v80
	v_cndmask_b32_e32 v81, v167, v82, vcc
	v_lshlrev_b32_e32 v81, 2, v81
	ds_bpermute_b32 v81, v81, v80
	s_and_saveexec_b64 s[38:39], s[4:5]
	s_cbranch_execz .LBB0_508
	v_lshlrev_b64 v[82:83], 7, v[184:185]
	v_lshl_add_u64 v[82:83], s[22:23], 0, v[82:83]
	v_lshl_add_u64 v[82:83], s[36:37], 2, v[82:83]
	s_lshl_b32 s2, s53, 2
	v_lshl_add_u64 v[82:83], v[82:83], 0, s[2:3]
	s_waitcnt lgkmcnt(0)
	v_add_f32_e32 v80, v80, v81
	global_store_dword v[82:83], v80, off

; __device__ __forceinline__ unsigned cvt_pk_bf16(float lo, float hi) { unsigned r; asm volatile("v_cvt_pk_bf16_f32 %0, %1, %2" : "=v"(r) : "v"(lo), "v"(hi)); return r; }
;     __device__ __forceinline__ void operator()(const f32x4 (&acc)[2][2][4][2], const Unit& u, int wr, int wc, int fr, int fq) const {
;     ...
;                 const int row = row0 + ai * HALF + m * 16;
;                 bf16_t* rowp = O + (size_t)row * ldc + col0;
;                 float ss = 0.f;
;                 const float rs = rsv[ai * 4 + m];
; #pragma unroll
;                 for (int bj = 0; bj < 2; ++bj) {
;                     f32x4 v0 = acc[ai][bj][m][0] * rs, v1 = acc[ai][bj][m][1] * rs;
;                     if (act == ACT_GELU_VSS) {
;                         f32x2 a = gelu_pk((f32x2){v0[0], v0[1]}), b = gelu_pk((f32x2){v0[2], v0[3]}), c = gelu_pk((f32x2){v1[0], v1[1]}), d = gelu_pk((f32x2){v1[2], v1[3]});
;                         v0 = (f32x4){a.x, a.y, b.x, b.y}; v1 = (f32x4){c.x, c.y, d.x, d.y};
;                         ss += (v0[0] * v0[0] + v0[1] * v0[1]) + (v0[2] * v0[2] + v0[3] * v0[3]) + (v1[0] * v1[0] + v1[1] * v1[1]) + (v1[2] * v1[2] + v1[3] * v1[3]);
;                     } else if (act == ACT_RELU2) {
; #pragma unroll
;                         for (int j = 0; j < 4; ++j) { const float a = fmaxf(v0[j], 0.f), b = fmaxf(v1[j], 0.f); v0[j] = a * a; v1[j] = b * b; }
;                     } else if (act == ACT_COLSCALE) {
;                         v0 = v0 * *(const f32x4*)(colscale + col0 + bj * HALF); v1 = v1 * *(const f32x4*)(colscale + col0 + bj * HALF + 4);
;                     }
;                     u32x4 w; w.x = cvt_pk_bf16(v0[0], v0[1]); w.y = cvt_pk_bf16(v0[2], v0[3]); w.z = cvt_pk_bf16(v1[0], v1[1]); w.w = cvt_pk_bf16(v1[2], v1[3]);
;                     *(u32x4*)(rowp + bj * HALF) = w;
.LBB0_519:
	v_mad_u64_u32 v[72:73], s[38:39], v182, s42, 0
	v_mov_b32_e32 v74, v73
	v_mad_u64_u32 v[74:75], s[38:39], v183, s42, v[74:75]
	v_mov_b32_e32 v73, v74
	v_lshl_add_u64 v[72:73], v[72:73], 1, s[20:21]
	v_lshl_add_u64 v[72:73], v[130:131], 1, v[72:73]
	v_cvt_pk_bf16_f32 v74, v82, v83
	s_waitcnt lgkmcnt(0)
	v_cvt_pk_bf16_f32 v75, v80, v81
	v_cvt_pk_bf16_f32 v76, v86, v87
	v_cvt_pk_bf16_f32 v77, v84, v85
	v_mov_b32_e32 v210, v74
	v_mov_b32_e32 v211, v75
	v_mov_b32_e32 v212, v76
	v_mov_b32_e32 v213, v77
	v_mov_b32_e32 v187, v186
	v_pk_mul_f32 v[68:69], v[68:69], v[186:187]
	v_mov_b32_e32 v74, v186
	v_mov_b32_e32 v75, v186
	v_pk_mul_f32 v[70:71], v[70:71], v[74:75]
	v_pk_mul_f32 v[66:67], v[66:67], v[74:75]
	v_pk_mul_f32 v[64:65], v[64:65], v[186:187]
	s_cmp_lt_i32 s43, 2
	s_mov_b64 s[38:39], -1
	s_cbranch_scc1 .LBB0_525
	s_cmp_gt_i32 s43, 2
	s_cbranch_scc0 .LBB0_522
	v_lshl_add_u64 v[74:75], v[130:131], 2, s[96:97]
	global_load_dwordx4 v[76:79], v[74:75], off offset:128
	global_load_dwordx4 v[80:83], v[74:75], off offset:144
	s_mov_b64 s[38:39], 0
	s_waitcnt vmcnt(0)
	v_pk_mul_f32 v[74:75], v[70:71], v[78:79]
	v_pk_mul_f32 v[76:77], v[68:69], v[76:77]
	v_pk_mul_f32 v[78:79], v[66:67], v[82:83]
	v_pk_mul_f32 v[80:81], v[64:65], v[80:81]

; __device__ __forceinline__ unsigned cvt_pk_bf16(float lo, float hi) { unsigned r; asm volatile("v_cvt_pk_bf16_f32 %0, %1, %2" : "=v"(r) : "v"(lo), "v"(hi)); return r; }
;     __device__ __forceinline__ void operator()(const f32x4 (&acc)[2][2][4][2], const Unit& u, int wr, int wc, int fr, int fq) const {
;     ...
;                     u32x4 w; w.x = cvt_pk_bf16(v0[0], v0[1]); w.y = cvt_pk_bf16(v0[2], v0[3]); w.z = cvt_pk_bf16(v1[0], v1[1]); w.w = cvt_pk_bf16(v1[2], v1[3]);
;                     *(u32x4*)(rowp + bj * HALF) = w;
;                 }
;                 if (do_vss) { ss += __shfl_xor(ss, 16); ss += __shfl_xor(ss, 32); if (fq == 0) vss[(size_t)row * 32 + (u.pn - 8) * 4 + wc] = ss; }
.LBB0_529:
	s_and_b64 vcc, exec, s[0:1]
	v_cvt_pk_bf16_f32 v64, v76, v77
	v_cvt_pk_bf16_f32 v65, v74, v75
	v_cvt_pk_bf16_f32 v66, v80, v81
	v_cvt_pk_bf16_f32 v67, v78, v79
	s_nop 1
	v_mov_b32_dpp v214, v64 row_ror:8 row_mask:0xf bank_mask:0xf
	v_mov_b32_dpp v215, v65 row_ror:8 row_mask:0xf bank_mask:0xf
	v_mov_b32_dpp v216, v66 row_ror:8 row_mask:0xf bank_mask:0xf
	v_mov_b32_dpp v217, v67 row_ror:8 row_mask:0xf bank_mask:0xf
	v_bfi_b32 v218, v235, v210, v214
	v_bfi_b32 v219, v235, v211, v215
	v_bfi_b32 v220, v235, v212, v216
	v_bfi_b32 v221, v235, v213, v217
	v_bfi_b32 v222, v235, v214, v210
	v_bfi_b32 v223, v235, v215, v211
	v_bfi_b32 v224, v235, v216, v212
	v_bfi_b32 v225, v235, v217, v213
	v_lshl_add_u64 v[230:231], v[72:73], 0, v[226:227]
	v_lshl_add_u64 v[232:233], v[72:73], 0, v[228:229]
	global_store_dwordx4 v[230:231], v[218:221], off
	global_store_dwordx4 v[232:233], v[222:225], off
	s_cbranch_vccnz .LBB0_533
	s_nop 0
	v_and_b32_e32 v65, 64, v167
	v_xor_b32_e32 v64, 16, v167
	v_add_u32_e32 v65, 64, v65
	v_cmp_lt_i32_e32 vcc, v64, v65
	v_xor_b32_e32 v66, 32, v167
	s_nop 0
	v_cndmask_b32_e32 v64, v167, v64, vcc
	v_lshlrev_b32_e32 v64, 2, v64
	ds_bpermute_b32 v64, v64, v88
	v_cmp_lt_i32_e32 vcc, v66, v65
	s_waitcnt lgkmcnt(0)
	v_add_f32_e32 v64, v88, v64
	v_cndmask_b32_e32 v65, v167, v66, vcc
	v_lshlrev_b32_e32 v65, 2, v65
	ds_bpermute_b32 v65, v65, v64
	s_and_saveexec_b64 s[38:39], s[4:5]
	s_cbranch_execz .LBB0_532
	v_lshlrev_b64 v[66:67], 7, v[182:183]
	v_lshl_add_u64 v[66:67], s[22:23], 0, v[66:67]
	v_lshl_add_u64 v[66:67], s[36:37], 2, v[66:67]
	s_lshl_b32 s2, s53, 2
	v_lshl_add_u64 v[66:67], v[66:67], 0, s[2:3]
	s_waitcnt lgkmcnt(0)
	v_add_f32_e32 v64, v64, v65
	global_store_dword v[66:67], v64, off

; __device__ __forceinline__ unsigned cvt_pk_bf16(float lo, float hi) { unsigned r; asm volatile("v_cvt_pk_bf16_f32 %0, %1, %2" : "=v"(r) : "v"(lo), "v"(hi)); return r; }
;     __device__ __forceinline__ void operator()(const f32x4 (&acc)[2][2][4][2], const Unit& u, int wr, int wc, int fr, int fq) const {
;     ...
;                 const int row = row0 + ai * HALF + m * 16;
;                 bf16_t* rowp = O + (size_t)row * ldc + col0;
;                 float ss = 0.f;
;                 const float rs = rsv[ai * 4 + m];
; #pragma unroll
;                 for (int bj = 0; bj < 2; ++bj) {
;                     f32x4 v0 = acc[ai][bj][m][0] * rs, v1 = acc[ai][bj][m][1] * rs;
;                     if (act == ACT_GELU_VSS) {
;                         f32x2 a = gelu_pk((f32x2){v0[0], v0[1]}), b = gelu_pk((f32x2){v0[2], v0[3]}), c = gelu_pk((f32x2){v1[0], v1[1]}), d = gelu_pk((f32x2){v1[2], v1[3]});
;                         v0 = (f32x4){a.x, a.y, b.x, b.y}; v1 = (f32x4){c.x, c.y, d.x, d.y};
;                         ss += (v0[0] * v0[0] + v0[1] * v0[1]) + (v0[2] * v0[2] + v0[3] * v0[3]) + (v1[0] * v1[0] + v1[1] * v1[1]) + (v1[2] * v1[2] + v1[3] * v1[3]);
;                     } else if (act == ACT_RELU2) {
; #pragma unroll
;                         for (int j = 0; j < 4; ++j) { const float a = fmaxf(v0[j], 0.f), b = fmaxf(v1[j], 0.f); v0[j] = a * a; v1[j] = b * b; }
;                     } else if (act == ACT_COLSCALE) {
;                         v0 = v0 * *(const f32x4*)(colscale + col0 + bj * HALF); v1 = v1 * *(const f32x4*)(colscale + col0 + bj * HALF + 4);
;                     }
;                     u32x4 w; w.x = cvt_pk_bf16(v0[0], v0[1]); w.y = cvt_pk_bf16(v0[2], v0[3]); w.z = cvt_pk_bf16(v1[0], v1[1]); w.w = cvt_pk_bf16(v1[2], v1[3]);
;                     *(u32x4*)(rowp + bj * HALF) = w;
.LBB0_543:
	v_add_u32_e32 v56, 0x80, v180
	v_mad_u64_u32 v[58:59], s[38:39], v56, s42, 0
	v_ashrrev_i32_e32 v57, 31, v56
	v_mov_b32_e32 v60, v59
	v_mad_u64_u32 v[60:61], s[38:39], v57, s42, v[60:61]
	v_mov_b32_e32 v59, v60
	v_lshl_add_u64 v[58:59], v[58:59], 1, s[20:21]
	v_lshl_add_u64 v[58:59], v[130:131], 1, v[58:59]
	v_cvt_pk_bf16_f32 v60, v66, v67
	s_waitcnt lgkmcnt(0)
	v_cvt_pk_bf16_f32 v61, v64, v65
	v_cvt_pk_bf16_f32 v62, v70, v71
	v_cvt_pk_bf16_f32 v63, v68, v69
	v_mov_b32_e32 v210, v60
	v_mov_b32_e32 v211, v61
	v_mov_b32_e32 v212, v62
	v_mov_b32_e32 v213, v63
	v_mov_b32_e32 v147, v146
	v_pk_mul_f32 v[52:53], v[52:53], v[146:147]
	v_mov_b32_e32 v60, v146
	v_mov_b32_e32 v61, v146
	v_pk_mul_f32 v[54:55], v[54:55], v[60:61]
	v_pk_mul_f32 v[50:51], v[50:51], v[60:61]
	v_pk_mul_f32 v[48:49], v[48:49], v[146:147]
	s_cmp_lt_i32 s43, 2
	s_mov_b64 s[38:39], -1
	s_cbranch_scc1 .LBB0_549
	s_cmp_gt_i32 s43, 2
	s_cbranch_scc0 .LBB0_546
	v_lshl_add_u64 v[60:61], v[130:131], 2, s[96:97]
	global_load_dwordx4 v[62:65], v[60:61], off offset:128
	global_load_dwordx4 v[66:69], v[60:61], off offset:144
	s_mov_b64 s[38:39], 0
	s_waitcnt vmcnt(0)
	v_pk_mul_f32 v[60:61], v[54:55], v[64:65]
	v_pk_mul_f32 v[62:63], v[52:53], v[62:63]
	v_pk_mul_f32 v[64:65], v[50:51], v[68:69]
	v_pk_mul_f32 v[66:67], v[48:49], v[66:67]

; __device__ __forceinline__ unsigned cvt_pk_bf16(float lo, float hi) { unsigned r; asm volatile("v_cvt_pk_bf16_f32 %0, %1, %2" : "=v"(r) : "v"(lo), "v"(hi)); return r; }
;     __device__ __forceinline__ void operator()(const f32x4 (&acc)[2][2][4][2], const Unit& u, int wr, int wc, int fr, int fq) const {
;     ...
;                     u32x4 w; w.x = cvt_pk_bf16(v0[0], v0[1]); w.y = cvt_pk_bf16(v0[2], v0[3]); w.z = cvt_pk_bf16(v1[0], v1[1]); w.w = cvt_pk_bf16(v1[2], v1[3]);
;                     *(u32x4*)(rowp + bj * HALF) = w;
;                 }
;                 if (do_vss) { ss += __shfl_xor(ss, 16); ss += __shfl_xor(ss, 32); if (fq == 0) vss[(size_t)row * 32 + (u.pn - 8) * 4 + wc] = ss; }
.LBB0_553:
	s_and_b64 vcc, exec, s[0:1]
	v_cvt_pk_bf16_f32 v48, v62, v63
	v_cvt_pk_bf16_f32 v49, v60, v61
	v_cvt_pk_bf16_f32 v50, v66, v67
	v_cvt_pk_bf16_f32 v51, v64, v65
	s_nop 1
	v_mov_b32_dpp v214, v48 row_ror:8 row_mask:0xf bank_mask:0xf
	v_mov_b32_dpp v215, v49 row_ror:8 row_mask:0xf bank_mask:0xf
	v_mov_b32_dpp v216, v50 row_ror:8 row_mask:0xf bank_mask:0xf
	v_mov_b32_dpp v217, v51 row_ror:8 row_mask:0xf bank_mask:0xf
	v_bfi_b32 v218, v235, v210, v214
	v_bfi_b32 v219, v235, v211, v215
	v_bfi_b32 v220, v235, v212, v216
	v_bfi_b32 v221, v235, v213, v217
	v_bfi_b32 v222, v235, v214, v210
	v_bfi_b32 v223, v235, v215, v211
	v_bfi_b32 v224, v235, v216, v212
	v_bfi_b32 v225, v235, v217, v213
	v_lshl_add_u64 v[230:231], v[58:59], 0, v[226:227]
	v_lshl_add_u64 v[232:233], v[58:59], 0, v[228:229]
	global_store_dwordx4 v[230:231], v[218:221], off
	global_store_dwordx4 v[232:233], v[222:225], off
	s_cbranch_vccnz .LBB0_557
	s_nop 0
	v_and_b32_e32 v49, 64, v167
	v_xor_b32_e32 v48, 16, v167
	v_add_u32_e32 v49, 64, v49
	v_cmp_lt_i32_e32 vcc, v48, v49
	v_xor_b32_e32 v50, 32, v167
	s_nop 0
	v_cndmask_b32_e32 v48, v167, v48, vcc
	v_lshlrev_b32_e32 v48, 2, v48
	ds_bpermute_b32 v48, v48, v72
	v_cmp_lt_i32_e32 vcc, v50, v49
	s_waitcnt lgkmcnt(0)
	v_add_f32_e32 v48, v72, v48
	v_cndmask_b32_e32 v49, v167, v50, vcc
	v_lshlrev_b32_e32 v49, 2, v49
	ds_bpermute_b32 v49, v49, v48
	s_and_saveexec_b64 s[38:39], s[4:5]
	s_cbranch_execz .LBB0_556
	v_lshlrev_b64 v[50:51], 7, v[56:57]
	v_lshl_add_u64 v[50:51], s[22:23], 0, v[50:51]
	v_lshl_add_u64 v[50:51], s[36:37], 2, v[50:51]
	s_lshl_b32 s2, s53, 2
	v_lshl_add_u64 v[50:51], v[50:51], 0, s[2:3]
	s_waitcnt lgkmcnt(0)
	v_add_f32_e32 v48, v48, v49
	global_store_dword v[50:51], v48, off

; __device__ __forceinline__ unsigned cvt_pk_bf16(float lo, float hi) { unsigned r; asm volatile("v_cvt_pk_bf16_f32 %0, %1, %2" : "=v"(r) : "v"(lo), "v"(hi)); return r; }
;     __device__ __forceinline__ void operator()(const f32x4 (&acc)[2][2][4][2], const Unit& u, int wr, int wc, int fr, int fq) const {
;     ...
;                 const int row = row0 + ai * HALF + m * 16;
;                 bf16_t* rowp = O + (size_t)row * ldc + col0;
;                 float ss = 0.f;
;                 const float rs = rsv[ai * 4 + m];
; #pragma unroll
;                 for (int bj = 0; bj < 2; ++bj) {
;                     f32x4 v0 = acc[ai][bj][m][0] * rs, v1 = acc[ai][bj][m][1] * rs;
;                     if (act == ACT_GELU_VSS) {
;                         f32x2 a = gelu_pk((f32x2){v0[0], v0[1]}), b = gelu_pk((f32x2){v0[2], v0[3]}), c = gelu_pk((f32x2){v1[0], v1[1]}), d = gelu_pk((f32x2){v1[2], v1[3]});
;                         v0 = (f32x4){a.x, a.y, b.x, b.y}; v1 = (f32x4){c.x, c.y, d.x, d.y};
;                         ss += (v0[0] * v0[0] + v0[1] * v0[1]) + (v0[2] * v0[2] + v0[3] * v0[3]) + (v1[0] * v1[0] + v1[1] * v1[1]) + (v1[2] * v1[2] + v1[3] * v1[3]);
;                     } else if (act == ACT_RELU2) {
; #pragma unroll
;                         for (int j = 0; j < 4; ++j) { const float a = fmaxf(v0[j], 0.f), b = fmaxf(v1[j], 0.f); v0[j] = a * a; v1[j] = b * b; }
;                     } else if (act == ACT_COLSCALE) {
;                         v0 = v0 * *(const f32x4*)(colscale + col0 + bj * HALF); v1 = v1 * *(const f32x4*)(colscale + col0 + bj * HALF + 4);
;                     }
;                     u32x4 w; w.x = cvt_pk_bf16(v0[0], v0[1]); w.y = cvt_pk_bf16(v0[2], v0[3]); w.z = cvt_pk_bf16(v1[0], v1[1]); w.w = cvt_pk_bf16(v1[2], v1[3]);
;                     *(u32x4*)(rowp + bj * HALF) = w;
.LBB0_567:
	v_add_u32_e32 v40, 0x90, v180
	v_mad_u64_u32 v[42:43], s[38:39], v40, s42, 0
	v_ashrrev_i32_e32 v41, 31, v40
	v_mov_b32_e32 v44, v43
	v_mad_u64_u32 v[44:45], s[38:39], v41, s42, v[44:45]
	v_mov_b32_e32 v43, v44
	v_lshl_add_u64 v[42:43], v[42:43], 1, s[20:21]
	v_lshl_add_u64 v[42:43], v[130:131], 1, v[42:43]
	v_cvt_pk_bf16_f32 v44, v50, v51
	s_waitcnt lgkmcnt(0)
	v_cvt_pk_bf16_f32 v45, v48, v49
	v_cvt_pk_bf16_f32 v46, v54, v55
	v_cvt_pk_bf16_f32 v47, v52, v53
	v_mov_b32_e32 v210, v44
	v_mov_b32_e32 v211, v45
	v_mov_b32_e32 v212, v46
	v_mov_b32_e32 v213, v47
	v_mov_b32_e32 v145, v144
	v_pk_mul_f32 v[36:37], v[36:37], v[144:145]
	v_mov_b32_e32 v44, v144
	v_mov_b32_e32 v45, v144
	v_pk_mul_f32 v[38:39], v[38:39], v[44:45]
	v_pk_mul_f32 v[34:35], v[34:35], v[44:45]
	v_pk_mul_f32 v[32:33], v[32:33], v[144:145]
	s_cmp_lt_i32 s43, 2
	s_mov_b64 s[38:39], -1
	s_cbranch_scc1 .LBB0_573
	s_cmp_gt_i32 s43, 2
	s_cbranch_scc0 .LBB0_570
	v_lshl_add_u64 v[44:45], v[130:131], 2, s[96:97]
	global_load_dwordx4 v[46:49], v[44:45], off offset:128
	global_load_dwordx4 v[50:53], v[44:45], off offset:144
	s_mov_b64 s[38:39], 0
	s_waitcnt vmcnt(0)
	v_pk_mul_f32 v[44:45], v[38:39], v[48:49]
	v_pk_mul_f32 v[46:47], v[36:37], v[46:47]
	v_pk_mul_f32 v[48:49], v[34:35], v[52:53]
	v_pk_mul_f32 v[50:51], v[32:33], v[50:51]

; __device__ __forceinline__ unsigned cvt_pk_bf16(float lo, float hi) { unsigned r; asm volatile("v_cvt_pk_bf16_f32 %0, %1, %2" : "=v"(r) : "v"(lo), "v"(hi)); return r; }
;     __device__ __forceinline__ void operator()(const f32x4 (&acc)[2][2][4][2], const Unit& u, int wr, int wc, int fr, int fq) const {
;     ...
;                     u32x4 w; w.x = cvt_pk_bf16(v0[0], v0[1]); w.y = cvt_pk_bf16(v0[2], v0[3]); w.z = cvt_pk_bf16(v1[0], v1[1]); w.w = cvt_pk_bf16(v1[2], v1[3]);
;                     *(u32x4*)(rowp + bj * HALF) = w;
;                 }
;                 if (do_vss) { ss += __shfl_xor(ss, 16); ss += __shfl_xor(ss, 32); if (fq == 0) vss[(size_t)row * 32 + (u.pn - 8) * 4 + wc] = ss; }
.LBB0_577:
	s_and_b64 vcc, exec, s[0:1]
	v_cvt_pk_bf16_f32 v32, v46, v47
	v_cvt_pk_bf16_f32 v33, v44, v45
	v_cvt_pk_bf16_f32 v34, v50, v51
	v_cvt_pk_bf16_f32 v35, v48, v49
	s_nop 1
	v_mov_b32_dpp v214, v32 row_ror:8 row_mask:0xf bank_mask:0xf
	v_mov_b32_dpp v215, v33 row_ror:8 row_mask:0xf bank_mask:0xf
	v_mov_b32_dpp v216, v34 row_ror:8 row_mask:0xf bank_mask:0xf
	v_mov_b32_dpp v217, v35 row_ror:8 row_mask:0xf bank_mask:0xf
	v_bfi_b32 v218, v235, v210, v214
	v_bfi_b32 v219, v235, v211, v215
	v_bfi_b32 v220, v235, v212, v216
	v_bfi_b32 v221, v235, v213, v217
	v_bfi_b32 v222, v235, v214, v210
	v_bfi_b32 v223, v235, v215, v211
	v_bfi_b32 v224, v235, v216, v212
	v_bfi_b32 v225, v235, v217, v213
	v_lshl_add_u64 v[230:231], v[42:43], 0, v[226:227]
	v_lshl_add_u64 v[232:233], v[42:43], 0, v[228:229]
	global_store_dwordx4 v[230:231], v[218:221], off
	global_store_dwordx4 v[232:233], v[222:225], off
	s_cbranch_vccnz .LBB0_581
	s_nop 0
	v_and_b32_e32 v33, 64, v167
	v_xor_b32_e32 v32, 16, v167
	v_add_u32_e32 v33, 64, v33
	v_cmp_lt_i32_e32 vcc, v32, v33
	v_xor_b32_e32 v34, 32, v167
	s_nop 0
	v_cndmask_b32_e32 v32, v167, v32, vcc
	v_lshlrev_b32_e32 v32, 2, v32
	ds_bpermute_b32 v32, v32, v56
	v_cmp_lt_i32_e32 vcc, v34, v33
	s_waitcnt lgkmcnt(0)
	v_add_f32_e32 v32, v56, v32
	v_cndmask_b32_e32 v33, v167, v34, vcc
	v_lshlrev_b32_e32 v33, 2, v33
	ds_bpermute_b32 v33, v33, v32
	s_and_saveexec_b64 s[38:39], s[4:5]
	s_cbranch_execz .LBB0_580
	v_lshlrev_b64 v[34:35], 7, v[40:41]
	v_lshl_add_u64 v[34:35], s[22:23], 0, v[34:35]
	v_lshl_add_u64 v[34:35], s[36:37], 2, v[34:35]
	s_lshl_b32 s2, s53, 2
	v_lshl_add_u64 v[34:35], v[34:35], 0, s[2:3]
	s_waitcnt lgkmcnt(0)
	v_add_f32_e32 v32, v32, v33
	global_store_dword v[34:35], v32, off

; __device__ __forceinline__ unsigned cvt_pk_bf16(float lo, float hi) { unsigned r; asm volatile("v_cvt_pk_bf16_f32 %0, %1, %2" : "=v"(r) : "v"(lo), "v"(hi)); return r; }
;     __device__ __forceinline__ void operator()(const f32x4 (&acc)[2][2][4][2], const Unit& u, int wr, int wc, int fr, int fq) const {
;     ...
;                 const int row = row0 + ai * HALF + m * 16;
;                 bf16_t* rowp = O + (size_t)row * ldc + col0;
;                 float ss = 0.f;
;                 const float rs = rsv[ai * 4 + m];
; #pragma unroll
;                 for (int bj = 0; bj < 2; ++bj) {
;                     f32x4 v0 = acc[ai][bj][m][0] * rs, v1 = acc[ai][bj][m][1] * rs;
;                     if (act == ACT_GELU_VSS) {
;                         f32x2 a = gelu_pk((f32x2){v0[0], v0[1]}), b = gelu_pk((f32x2){v0[2], v0[3]}), c = gelu_pk((f32x2){v1[0], v1[1]}), d = gelu_pk((f32x2){v1[2], v1[3]});
;                         v0 = (f32x4){a.x, a.y, b.x, b.y}; v1 = (f32x4){c.x, c.y, d.x, d.y};
;                         ss += (v0[0] * v0[0] + v0[1] * v0[1]) + (v0[2] * v0[2] + v0[3] * v0[3]) + (v1[0] * v1[0] + v1[1] * v1[1]) + (v1[2] * v1[2] + v1[3] * v1[3]);
;                     } else if (act == ACT_RELU2) {
; #pragma unroll
;                         for (int j = 0; j < 4; ++j) { const float a = fmaxf(v0[j], 0.f), b = fmaxf(v1[j], 0.f); v0[j] = a * a; v1[j] = b * b; }
;                     } else if (act == ACT_COLSCALE) {
;                         v0 = v0 * *(const f32x4*)(colscale + col0 + bj * HALF); v1 = v1 * *(const f32x4*)(colscale + col0 + bj * HALF + 4);
;                     }
;                     u32x4 w; w.x = cvt_pk_bf16(v0[0], v0[1]); w.y = cvt_pk_bf16(v0[2], v0[3]); w.z = cvt_pk_bf16(v1[0], v1[1]); w.w = cvt_pk_bf16(v1[2], v1[3]);
;                     *(u32x4*)(rowp + bj * HALF) = w;
.LBB0_591:
	v_add_u32_e32 v24, 0xa0, v180
	v_mad_u64_u32 v[26:27], s[38:39], v24, s42, 0
	v_ashrrev_i32_e32 v25, 31, v24
	v_mov_b32_e32 v28, v27
	v_mad_u64_u32 v[28:29], s[38:39], v25, s42, v[28:29]
	v_mov_b32_e32 v27, v28
	v_lshl_add_u64 v[26:27], v[26:27], 1, s[20:21]
	v_lshl_add_u64 v[26:27], v[130:131], 1, v[26:27]
	v_cvt_pk_bf16_f32 v28, v34, v35
	s_waitcnt lgkmcnt(0)
	v_cvt_pk_bf16_f32 v29, v32, v33
	v_cvt_pk_bf16_f32 v30, v38, v39
	v_cvt_pk_bf16_f32 v31, v36, v37
	v_mov_b32_e32 v210, v28
	v_mov_b32_e32 v211, v29
	v_mov_b32_e32 v212, v30
	v_mov_b32_e32 v213, v31
	v_mov_b32_e32 v137, v136
	v_pk_mul_f32 v[20:21], v[20:21], v[136:137]
	v_mov_b32_e32 v28, v136
	v_mov_b32_e32 v29, v136
	v_pk_mul_f32 v[22:23], v[22:23], v[28:29]
	v_pk_mul_f32 v[18:19], v[18:19], v[28:29]
	v_pk_mul_f32 v[16:17], v[16:17], v[136:137]
	s_cmp_lt_i32 s43, 2
	s_mov_b64 s[38:39], -1
	s_cbranch_scc1 .LBB0_597
	s_cmp_gt_i32 s43, 2
	s_cbranch_scc0 .LBB0_594
	v_lshl_add_u64 v[28:29], v[130:131], 2, s[96:97]
	global_load_dwordx4 v[30:33], v[28:29], off offset:128
	global_load_dwordx4 v[34:37], v[28:29], off offset:144
	s_mov_b64 s[38:39], 0
	s_waitcnt vmcnt(0)
	v_pk_mul_f32 v[28:29], v[22:23], v[32:33]
	v_pk_mul_f32 v[30:31], v[20:21], v[30:31]
	v_pk_mul_f32 v[32:33], v[18:19], v[36:37]
	v_pk_mul_f32 v[34:35], v[16:17], v[34:35]

; __device__ __forceinline__ unsigned cvt_pk_bf16(float lo, float hi) { unsigned r; asm volatile("v_cvt_pk_bf16_f32 %0, %1, %2" : "=v"(r) : "v"(lo), "v"(hi)); return r; }
;     __device__ __forceinline__ void operator()(const f32x4 (&acc)[2][2][4][2], const Unit& u, int wr, int wc, int fr, int fq) const {
;     ...
;                     u32x4 w; w.x = cvt_pk_bf16(v0[0], v0[1]); w.y = cvt_pk_bf16(v0[2], v0[3]); w.z = cvt_pk_bf16(v1[0], v1[1]); w.w = cvt_pk_bf16(v1[2], v1[3]);
;                     *(u32x4*)(rowp + bj * HALF) = w;
;                 }
;                 if (do_vss) { ss += __shfl_xor(ss, 16); ss += __shfl_xor(ss, 32); if (fq == 0) vss[(size_t)row * 32 + (u.pn - 8) * 4 + wc] = ss; }
.LBB0_601:
	s_and_b64 vcc, exec, s[0:1]
	v_cvt_pk_bf16_f32 v16, v30, v31
	v_cvt_pk_bf16_f32 v17, v28, v29
	v_cvt_pk_bf16_f32 v18, v34, v35
	v_cvt_pk_bf16_f32 v19, v32, v33
	s_nop 1
	v_mov_b32_dpp v214, v16 row_ror:8 row_mask:0xf bank_mask:0xf
	v_mov_b32_dpp v215, v17 row_ror:8 row_mask:0xf bank_mask:0xf
	v_mov_b32_dpp v216, v18 row_ror:8 row_mask:0xf bank_mask:0xf
	v_mov_b32_dpp v217, v19 row_ror:8 row_mask:0xf bank_mask:0xf
	v_bfi_b32 v218, v235, v210, v214
	v_bfi_b32 v219, v235, v211, v215
	v_bfi_b32 v220, v235, v212, v216
	v_bfi_b32 v221, v235, v213, v217
	v_bfi_b32 v222, v235, v214, v210
	v_bfi_b32 v223, v235, v215, v211
	v_bfi_b32 v224, v235, v216, v212
	v_bfi_b32 v225, v235, v217, v213
	v_lshl_add_u64 v[230:231], v[26:27], 0, v[226:227]
	v_lshl_add_u64 v[232:233], v[26:27], 0, v[228:229]
	global_store_dwordx4 v[230:231], v[218:221], off
	global_store_dwordx4 v[232:233], v[222:225], off
	s_cbranch_vccnz .LBB0_605
	s_nop 0
	v_and_b32_e32 v17, 64, v167
	v_xor_b32_e32 v16, 16, v167
	v_add_u32_e32 v17, 64, v17
	v_cmp_lt_i32_e32 vcc, v16, v17
	v_xor_b32_e32 v18, 32, v167
	s_nop 0
	v_cndmask_b32_e32 v16, v167, v16, vcc
	v_lshlrev_b32_e32 v16, 2, v16
	ds_bpermute_b32 v16, v16, v40
	v_cmp_lt_i32_e32 vcc, v18, v17
	s_waitcnt lgkmcnt(0)
	v_add_f32_e32 v16, v40, v16
	v_cndmask_b32_e32 v17, v167, v18, vcc
	v_lshlrev_b32_e32 v17, 2, v17
	ds_bpermute_b32 v17, v17, v16
	s_and_saveexec_b64 s[38:39], s[4:5]
	s_cbranch_execz .LBB0_604
	v_lshlrev_b64 v[18:19], 7, v[24:25]
	v_lshl_add_u64 v[18:19], s[22:23], 0, v[18:19]
	v_lshl_add_u64 v[18:19], s[36:37], 2, v[18:19]
	s_lshl_b32 s2, s53, 2
	v_lshl_add_u64 v[18:19], v[18:19], 0, s[2:3]
	s_waitcnt lgkmcnt(0)
	v_add_f32_e32 v16, v16, v17
	global_store_dword v[18:19], v16, off

; __device__ __forceinline__ unsigned cvt_pk_bf16(float lo, float hi) { unsigned r; asm volatile("v_cvt_pk_bf16_f32 %0, %1, %2" : "=v"(r) : "v"(lo), "v"(hi)); return r; }
;     __device__ __forceinline__ void operator()(const f32x4 (&acc)[2][2][4][2], const Unit& u, int wr, int wc, int fr, int fq) const {
;     ...
;                 const int row = row0 + ai * HALF + m * 16;
;                 bf16_t* rowp = O + (size_t)row * ldc + col0;
;                 float ss = 0.f;
;                 const float rs = rsv[ai * 4 + m];
; #pragma unroll
;                 for (int bj = 0; bj < 2; ++bj) {
;                     f32x4 v0 = acc[ai][bj][m][0] * rs, v1 = acc[ai][bj][m][1] * rs;
;                     if (act == ACT_GELU_VSS) {
;                         f32x2 a = gelu_pk((f32x2){v0[0], v0[1]}), b = gelu_pk((f32x2){v0[2], v0[3]}), c = gelu_pk((f32x2){v1[0], v1[1]}), d = gelu_pk((f32x2){v1[2], v1[3]});
;                         v0 = (f32x4){a.x, a.y, b.x, b.y}; v1 = (f32x4){c.x, c.y, d.x, d.y};
;                         ss += (v0[0] * v0[0] + v0[1] * v0[1]) + (v0[2] * v0[2] + v0[3] * v0[3]) + (v1[0] * v1[0] + v1[1] * v1[1]) + (v1[2] * v1[2] + v1[3] * v1[3]);
;                     } else if (act == ACT_RELU2) {
; #pragma unroll
;                         for (int j = 0; j < 4; ++j) { const float a = fmaxf(v0[j], 0.f), b = fmaxf(v1[j], 0.f); v0[j] = a * a; v1[j] = b * b; }
;                     } else if (act == ACT_COLSCALE) {
;                         v0 = v0 * *(const f32x4*)(colscale + col0 + bj * HALF); v1 = v1 * *(const f32x4*)(colscale + col0 + bj * HALF + 4);
;                     }
;                     u32x4 w; w.x = cvt_pk_bf16(v0[0], v0[1]); w.y = cvt_pk_bf16(v0[2], v0[3]); w.z = cvt_pk_bf16(v1[0], v1[1]); w.w = cvt_pk_bf16(v1[2], v1[3]);
;                     *(u32x4*)(rowp + bj * HALF) = w;
.LBB0_615:
	v_add_u32_e32 v8, 0xb0, v180
	v_mad_u64_u32 v[10:11], s[38:39], v8, s42, 0
	v_ashrrev_i32_e32 v9, 31, v8
	v_mov_b32_e32 v12, v11
	v_mad_u64_u32 v[12:13], s[38:39], v9, s42, v[12:13]
	v_mov_b32_e32 v11, v12
	v_lshl_add_u64 v[10:11], v[10:11], 1, s[20:21]
	v_lshl_add_u64 v[10:11], v[130:131], 1, v[10:11]
	v_cvt_pk_bf16_f32 v12, v18, v19
	s_waitcnt lgkmcnt(0)
	v_cvt_pk_bf16_f32 v13, v16, v17
	v_cvt_pk_bf16_f32 v14, v22, v23
	v_cvt_pk_bf16_f32 v15, v20, v21
	v_mov_b32_e32 v210, v12
	v_mov_b32_e32 v211, v13
	v_mov_b32_e32 v212, v14
	v_mov_b32_e32 v213, v15
	v_mov_b32_e32 v129, v128
	v_pk_mul_f32 v[4:5], v[4:5], v[128:129]
	v_mov_b32_e32 v12, v128
	v_mov_b32_e32 v13, v128
	v_pk_mul_f32 v[6:7], v[6:7], v[12:13]
	v_pk_mul_f32 v[2:3], v[2:3], v[12:13]
	v_pk_mul_f32 v[0:1], v[0:1], v[128:129]
	s_cmp_lt_i32 s43, 2
	s_mov_b64 s[38:39], -1
	s_cbranch_scc1 .LBB0_621
	s_cmp_gt_i32 s43, 2
	s_cbranch_scc0 .LBB0_618
	v_lshl_add_u64 v[12:13], v[130:131], 2, s[96:97]
	global_load_dwordx4 v[14:17], v[12:13], off offset:128
	global_load_dwordx4 v[18:21], v[12:13], off offset:144
	s_mov_b64 s[38:39], 0
	s_waitcnt vmcnt(0)
	v_pk_mul_f32 v[12:13], v[6:7], v[16:17]
	v_pk_mul_f32 v[14:15], v[4:5], v[14:15]
	v_pk_mul_f32 v[16:17], v[2:3], v[20:21]
	v_pk_mul_f32 v[18:19], v[0:1], v[18:19]

; __device__ __forceinline__ unsigned cvt_pk_bf16(float lo, float hi) { unsigned r; asm volatile("v_cvt_pk_bf16_f32 %0, %1, %2" : "=v"(r) : "v"(lo), "v"(hi)); return r; }
;     __device__ __forceinline__ void operator()(const f32x4 (&acc)[2][2][4][2], const Unit& u, int wr, int wc, int fr, int fq) const {
;     ...
;                     u32x4 w; w.x = cvt_pk_bf16(v0[0], v0[1]); w.y = cvt_pk_bf16(v0[2], v0[3]); w.z = cvt_pk_bf16(v1[0], v1[1]); w.w = cvt_pk_bf16(v1[2], v1[3]);
;                     *(u32x4*)(rowp + bj * HALF) = w;
;                 }
;                 if (do_vss) { ss += __shfl_xor(ss, 16); ss += __shfl_xor(ss, 32); if (fq == 0) vss[(size_t)row * 32 + (u.pn - 8) * 4 + wc] = ss; }
.LBB0_625:
	s_and_b64 vcc, exec, s[0:1]
	v_cvt_pk_bf16_f32 v0, v14, v15
	v_cvt_pk_bf16_f32 v1, v12, v13
	v_cvt_pk_bf16_f32 v2, v18, v19
	v_cvt_pk_bf16_f32 v3, v16, v17
	s_nop 1
	v_mov_b32_dpp v214, v0 row_ror:8 row_mask:0xf bank_mask:0xf
	v_mov_b32_dpp v215, v1 row_ror:8 row_mask:0xf bank_mask:0xf
	v_mov_b32_dpp v216, v2 row_ror:8 row_mask:0xf bank_mask:0xf
	v_mov_b32_dpp v217, v3 row_ror:8 row_mask:0xf bank_mask:0xf
	v_bfi_b32 v218, v235, v210, v214
	v_bfi_b32 v219, v235, v211, v215
	v_bfi_b32 v220, v235, v212, v216
	v_bfi_b32 v221, v235, v213, v217
	v_bfi_b32 v222, v235, v214, v210
	v_bfi_b32 v223, v235, v215, v211
	v_bfi_b32 v224, v235, v216, v212
	v_bfi_b32 v225, v235, v217, v213
	v_lshl_add_u64 v[230:231], v[10:11], 0, v[226:227]
	v_lshl_add_u64 v[232:233], v[10:11], 0, v[228:229]
	global_store_dwordx4 v[230:231], v[218:221], off
	global_store_dwordx4 v[232:233], v[222:225], off
	s_cbranch_vccnz .LBB0_629
	s_nop 0
	v_and_b32_e32 v1, 64, v167
	v_xor_b32_e32 v0, 16, v167
	v_add_u32_e32 v1, 64, v1
	v_cmp_lt_i32_e32 vcc, v0, v1
	v_xor_b32_e32 v2, 32, v167
	s_nop 0
	v_cndmask_b32_e32 v0, v167, v0, vcc
	v_lshlrev_b32_e32 v0, 2, v0
	ds_bpermute_b32 v0, v0, v24
	v_cmp_lt_i32_e32 vcc, v2, v1
	s_waitcnt lgkmcnt(0)
	v_add_f32_e32 v0, v24, v0
	v_cndmask_b32_e32 v1, v167, v2, vcc
	v_lshlrev_b32_e32 v1, 2, v1
	ds_bpermute_b32 v1, v1, v0
	s_and_saveexec_b64 s[0:1], s[4:5]
	s_cbranch_execz .LBB0_628
	v_lshlrev_b64 v[2:3], 7, v[8:9]
	v_lshl_add_u64 v[2:3], s[22:23], 0, v[2:3]
	v_lshl_add_u64 v[2:3], s[36:37], 2, v[2:3]
	s_lshl_b32 s2, s53, 2
	v_lshl_add_u64 v[2:3], v[2:3], 0, s[2:3]
	s_waitcnt lgkmcnt(0)
	v_add_f32_e32 v0, v0, v1
	global_store_dword v[2:3], v0, off
